# layer-1 in-projection slot: 6 conversion tiles + 1 sleep quantum
# speedup vs baseline: 1.0109x; 1.0109x over previous
.Lcw_l1:
	v_readlane_b32 s28, v253, 20
	v_readlane_b32 s29, v253, 21
	s_nop 3
	s_add_u32 s28, s28, 0x2200000
	s_addc_u32 s29, s29, 0
	s_add_i32 s4, s2, 1408
	s_and_b32 s3, s4, 15
	s_lshr_b32 s5, s4, 4
	s_mul_i32 s17, s3, 0x220000
	s_lshl_b32 s20, s5, 8
	s_add_i32 s17, s17, s20
	s_add_u32 s6, s28, s17
	s_addc_u32 s7, s29, 0
	s_add_u32 s12, s6, 0x110000
	s_addc_u32 s13, s7, 0
	s_lshl_b32 s17, s5, 17
	s_lshl_b32 s20, s3, 7
	s_add_i32 s17, s17, s20
	s_add_u32 s16, s96, s17
	s_addc_u32 s17, s97, 0
	s_add_u32 s16, s16, 0xf000000
	s_addc_u32 s17, s17, 0
	global_load_dwordx4 v[140:143], v138, s[6:7]
	global_load_dwordx4 v[150:153], v138, s[12:13]
	s_waitcnt vmcnt(0)
	ds_write_b32 v123, v140 offset:0
	ds_write_b32 v123, v141 offset:4
	ds_write_b32 v123, v142 offset:8
	ds_write_b32 v123, v143 offset:12
	ds_write_b32 v123, v150 offset:8320
	ds_write_b32 v123, v151 offset:8324
	ds_write_b32 v123, v152 offset:8328
	ds_write_b32 v123, v153 offset:8332
	s_waitcnt lgkmcnt(0)
	s_barrier
	s_mov_b64 s[26:27], s[16:17]
	s_add_i32 s4, s2, 1536
	s_and_b32 s3, s4, 15
	s_lshr_b32 s5, s4, 4
	s_mul_i32 s17, s3, 0x220000
	s_lshl_b32 s20, s5, 8
	s_add_i32 s17, s17, s20
	s_add_u32 s6, s28, s17
	s_addc_u32 s7, s29, 0
	s_add_u32 s12, s6, 0x110000
	s_addc_u32 s13, s7, 0
	s_lshl_b32 s17, s5, 17
	s_lshl_b32 s20, s3, 7
	s_add_i32 s17, s17, s20
	s_add_u32 s16, s96, s17
	s_addc_u32 s17, s97, 0
	s_add_u32 s16, s16, 0xf000000
	s_addc_u32 s17, s17, 0
	global_load_dwordx4 v[140:143], v138, s[6:7]
	global_load_dwordx4 v[150:153], v138, s[12:13]
	ds_read_b32 v154, v136 offset:0
	ds_read_b32 v155, v136 offset:260
	ds_read_b32 v156, v136 offset:520
	ds_read_b32 v157, v136 offset:780
	ds_read_b32 v158, v136 offset:1040
	ds_read_b32 v159, v136 offset:1300
	ds_read_b32 v160, v136 offset:1560
	ds_read_b32 v161, v136 offset:1820
	s_waitcnt lgkmcnt(0)
	v_mul_f32_e32 v154, v235, v154
	v_mul_f32_e32 v155, v235, v155
	v_mul_f32_e32 v156, v235, v156
	v_mul_f32_e32 v157, v235, v157
	v_mul_f32_e32 v158, v235, v158
	v_mul_f32_e32 v159, v235, v159
	v_mul_f32_e32 v160, v235, v160
	v_mul_f32_e32 v161, v235, v161
	v_cvt_pk_bf16_f32 v204, v154, v155
	v_cvt_pk_bf16_f32 v205, v156, v157
	v_cvt_pk_bf16_f32 v206, v158, v159
	v_cvt_pk_bf16_f32 v207, v160, v161
	global_store_dwordx4 v137, v[204:207], s[26:27]
	s_barrier
	s_waitcnt vmcnt(0)
	ds_write_b32 v123, v140 offset:0
	ds_write_b32 v123, v141 offset:4
	ds_write_b32 v123, v142 offset:8
	ds_write_b32 v123, v143 offset:12
	ds_write_b32 v123, v150 offset:8320
	ds_write_b32 v123, v151 offset:8324
	ds_write_b32 v123, v152 offset:8328
	ds_write_b32 v123, v153 offset:8332
	s_waitcnt lgkmcnt(0)
	s_barrier
	s_mov_b64 s[26:27], s[16:17]
	s_add_i32 s4, s2, 1664
	s_and_b32 s3, s4, 15
	s_lshr_b32 s5, s4, 4
	s_mul_i32 s17, s3, 0x220000
	s_lshl_b32 s20, s5, 8
	s_add_i32 s17, s17, s20
	s_add_u32 s6, s28, s17
	s_addc_u32 s7, s29, 0
	s_add_u32 s12, s6, 0x110000
	s_addc_u32 s13, s7, 0
	s_lshl_b32 s17, s5, 17
	s_lshl_b32 s20, s3, 7
	s_add_i32 s17, s17, s20
	s_add_u32 s16, s96, s17
	s_addc_u32 s17, s97, 0
	s_add_u32 s16, s16, 0xf000000
	s_addc_u32 s17, s17, 0
	global_load_dwordx4 v[140:143], v138, s[6:7]
	global_load_dwordx4 v[150:153], v138, s[12:13]
	ds_read_b32 v154, v136 offset:0
	ds_read_b32 v155, v136 offset:260
	ds_read_b32 v156, v136 offset:520
	ds_read_b32 v157, v136 offset:780
	ds_read_b32 v158, v136 offset:1040
	ds_read_b32 v159, v136 offset:1300
	ds_read_b32 v160, v136 offset:1560
	ds_read_b32 v161, v136 offset:1820
	s_waitcnt lgkmcnt(0)
	v_mul_f32_e32 v154, v235, v154
	v_mul_f32_e32 v155, v235, v155
	v_mul_f32_e32 v156, v235, v156
	v_mul_f32_e32 v157, v235, v157
	v_mul_f32_e32 v158, v235, v158
	v_mul_f32_e32 v159, v235, v159
	v_mul_f32_e32 v160, v235, v160
	v_mul_f32_e32 v161, v235, v161
	v_cvt_pk_bf16_f32 v204, v154, v155
	v_cvt_pk_bf16_f32 v205, v156, v157
	v_cvt_pk_bf16_f32 v206, v158, v159
	v_cvt_pk_bf16_f32 v207, v160, v161
	global_store_dwordx4 v137, v[204:207], s[26:27]
	s_barrier
	s_waitcnt vmcnt(0)
	ds_write_b32 v123, v140 offset:0
	ds_write_b32 v123, v141 offset:4
	ds_write_b32 v123, v142 offset:8
	ds_write_b32 v123, v143 offset:12
	ds_write_b32 v123, v150 offset:8320
	ds_write_b32 v123, v151 offset:8324
	ds_write_b32 v123, v152 offset:8328
	ds_write_b32 v123, v153 offset:8332
	s_waitcnt lgkmcnt(0)
	s_barrier
	s_mov_b64 s[26:27], s[16:17]
	s_add_i32 s4, s2, 1792
	s_and_b32 s3, s4, 15
	s_lshr_b32 s5, s4, 4
	s_mul_i32 s17, s3, 0x220000
	s_lshl_b32 s20, s5, 8
	s_add_i32 s17, s17, s20
	s_add_u32 s6, s28, s17
	s_addc_u32 s7, s29, 0
	s_add_u32 s12, s6, 0x110000
	s_addc_u32 s13, s7, 0
	s_lshl_b32 s17, s5, 17
	s_lshl_b32 s20, s3, 7
	s_add_i32 s17, s17, s20
	s_add_u32 s16, s96, s17
	s_addc_u32 s17, s97, 0
	s_add_u32 s16, s16, 0xf000000
	s_addc_u32 s17, s17, 0
	global_load_dwordx4 v[140:143], v138, s[6:7]
	global_load_dwordx4 v[150:153], v138, s[12:13]
	ds_read_b32 v154, v136 offset:0
	ds_read_b32 v155, v136 offset:260
	ds_read_b32 v156, v136 offset:520
	ds_read_b32 v157, v136 offset:780
	ds_read_b32 v158, v136 offset:1040
	ds_read_b32 v159, v136 offset:1300
	ds_read_b32 v160, v136 offset:1560
	ds_read_b32 v161, v136 offset:1820
	s_waitcnt lgkmcnt(0)
	v_mul_f32_e32 v154, v235, v154
	v_mul_f32_e32 v155, v235, v155
	v_mul_f32_e32 v156, v235, v156
	v_mul_f32_e32 v157, v235, v157
	v_mul_f32_e32 v158, v235, v158
	v_mul_f32_e32 v159, v235, v159
	v_mul_f32_e32 v160, v235, v160
	v_mul_f32_e32 v161, v235, v161
	v_cvt_pk_bf16_f32 v204, v154, v155
	v_cvt_pk_bf16_f32 v205, v156, v157
	v_cvt_pk_bf16_f32 v206, v158, v159
	v_cvt_pk_bf16_f32 v207, v160, v161
	global_store_dwordx4 v137, v[204:207], s[26:27]
	s_barrier
	s_waitcnt vmcnt(0)
	ds_write_b32 v123, v140 offset:0
	ds_write_b32 v123, v141 offset:4
	ds_write_b32 v123, v142 offset:8
	ds_write_b32 v123, v143 offset:12
	ds_write_b32 v123, v150 offset:8320
	ds_write_b32 v123, v151 offset:8324
	ds_write_b32 v123, v152 offset:8328
	ds_write_b32 v123, v153 offset:8332
	s_waitcnt lgkmcnt(0)
	s_barrier
	s_mov_b64 s[26:27], s[16:17]
	s_add_i32 s4, s2, 1920
	s_and_b32 s3, s4, 15
	s_lshr_b32 s5, s4, 4
	s_mul_i32 s17, s3, 0x220000
	s_lshl_b32 s20, s5, 8
	s_add_i32 s17, s17, s20
	s_add_u32 s6, s28, s17
	s_addc_u32 s7, s29, 0
	s_add_u32 s12, s6, 0x110000
	s_addc_u32 s13, s7, 0
	s_lshl_b32 s17, s5, 17
	s_lshl_b32 s20, s3, 7
	s_add_i32 s17, s17, s20
	s_add_u32 s16, s96, s17
	s_addc_u32 s17, s97, 0
	s_add_u32 s16, s16, 0xf000000
	s_addc_u32 s17, s17, 0
	global_load_dwordx4 v[140:143], v138, s[6:7]
	global_load_dwordx4 v[150:153], v138, s[12:13]
	ds_read_b32 v154, v136 offset:0
	ds_read_b32 v155, v136 offset:260
	ds_read_b32 v156, v136 offset:520
	ds_read_b32 v157, v136 offset:780
	ds_read_b32 v158, v136 offset:1040
	ds_read_b32 v159, v136 offset:1300
	ds_read_b32 v160, v136 offset:1560
	ds_read_b32 v161, v136 offset:1820
	s_waitcnt lgkmcnt(0)
	v_mul_f32_e32 v154, v235, v154
	v_mul_f32_e32 v155, v235, v155
	v_mul_f32_e32 v156, v235, v156
	v_mul_f32_e32 v157, v235, v157
	v_mul_f32_e32 v158, v235, v158
	v_mul_f32_e32 v159, v235, v159
	v_mul_f32_e32 v160, v235, v160
	v_mul_f32_e32 v161, v235, v161
	v_cvt_pk_bf16_f32 v204, v154, v155
	v_cvt_pk_bf16_f32 v205, v156, v157
	v_cvt_pk_bf16_f32 v206, v158, v159
	v_cvt_pk_bf16_f32 v207, v160, v161
	global_store_dwordx4 v137, v[204:207], s[26:27]
	s_barrier
	s_waitcnt vmcnt(0)
	ds_write_b32 v123, v140 offset:0
	ds_write_b32 v123, v141 offset:4
	ds_write_b32 v123, v142 offset:8
	ds_write_b32 v123, v143 offset:12
	ds_write_b32 v123, v150 offset:8320
	ds_write_b32 v123, v151 offset:8324
	ds_write_b32 v123, v152 offset:8328
	ds_write_b32 v123, v153 offset:8332
	s_waitcnt lgkmcnt(0)
	s_barrier
	s_mov_b64 s[26:27], s[16:17]
	s_add_i32 s4, s2, 2048
	s_and_b32 s3, s4, 15
	s_lshr_b32 s5, s4, 4
	s_mul_i32 s17, s3, 0x220000
	s_lshl_b32 s20, s5, 8
	s_add_i32 s17, s17, s20
	s_add_u32 s6, s28, s17
	s_addc_u32 s7, s29, 0
	s_add_u32 s12, s6, 0x110000
	s_addc_u32 s13, s7, 0
	s_lshl_b32 s17, s5, 17
	s_lshl_b32 s20, s3, 7
	s_add_i32 s17, s17, s20
	s_add_u32 s16, s96, s17
	s_addc_u32 s17, s97, 0
	s_add_u32 s16, s16, 0xf000000
	s_addc_u32 s17, s17, 0
	global_load_dwordx4 v[140:143], v138, s[6:7]
	global_load_dwordx4 v[150:153], v138, s[12:13]
	ds_read_b32 v154, v136 offset:0
	ds_read_b32 v155, v136 offset:260
	ds_read_b32 v156, v136 offset:520
	ds_read_b32 v157, v136 offset:780
	ds_read_b32 v158, v136 offset:1040
	ds_read_b32 v159, v136 offset:1300
	ds_read_b32 v160, v136 offset:1560
	ds_read_b32 v161, v136 offset:1820
	s_waitcnt lgkmcnt(0)
	v_mul_f32_e32 v154, v235, v154
	v_mul_f32_e32 v155, v235, v155
	v_mul_f32_e32 v156, v235, v156
	v_mul_f32_e32 v157, v235, v157
	v_mul_f32_e32 v158, v235, v158
	v_mul_f32_e32 v159, v235, v159
	v_mul_f32_e32 v160, v235, v160
	v_mul_f32_e32 v161, v235, v161
	v_cvt_pk_bf16_f32 v204, v154, v155
	v_cvt_pk_bf16_f32 v205, v156, v157
	v_cvt_pk_bf16_f32 v206, v158, v159
	v_cvt_pk_bf16_f32 v207, v160, v161
	global_store_dwordx4 v137, v[204:207], s[26:27]
	s_barrier
	s_waitcnt vmcnt(0)
	ds_write_b32 v123, v140 offset:0
	ds_write_b32 v123, v141 offset:4
	ds_write_b32 v123, v142 offset:8
	ds_write_b32 v123, v143 offset:12
	ds_write_b32 v123, v150 offset:8320
	ds_write_b32 v123, v151 offset:8324
	ds_write_b32 v123, v152 offset:8328
	ds_write_b32 v123, v153 offset:8332
	s_waitcnt lgkmcnt(0)
	s_barrier
	s_mov_b64 s[26:27], s[16:17]
	ds_read_b32 v154, v136 offset:0
	ds_read_b32 v155, v136 offset:260
	ds_read_b32 v156, v136 offset:520
	ds_read_b32 v157, v136 offset:780
	ds_read_b32 v158, v136 offset:1040
	ds_read_b32 v159, v136 offset:1300
	ds_read_b32 v160, v136 offset:1560
	ds_read_b32 v161, v136 offset:1820
	s_waitcnt lgkmcnt(0)
	v_mul_f32_e32 v154, v235, v154
	v_mul_f32_e32 v155, v235, v155
	v_mul_f32_e32 v156, v235, v156
	v_mul_f32_e32 v157, v235, v157
	v_mul_f32_e32 v158, v235, v158
	v_mul_f32_e32 v159, v235, v159
	v_mul_f32_e32 v160, v235, v160
	v_mul_f32_e32 v161, v235, v161
	v_cvt_pk_bf16_f32 v204, v154, v155
	v_cvt_pk_bf16_f32 v205, v156, v157
	v_cvt_pk_bf16_f32 v206, v158, v159
	v_cvt_pk_bf16_f32 v207, v160, v161
	global_store_dwordx4 v137, v[204:207], s[26:27]
	s_barrier
	s_sleep 0x7f
